# reversed FFN-down order and regenerated SwiGLU epilogue, activation stores keep the nt hint
# baseline (speedup 1.0000x reference)
.Lg131_nox:
	v_lshl_add_u32 v180, s51, 10, v147
	ds_read2_b32 v[152:153], v180 offset1:16
	ds_read2_b32 v[154:155], v180 offset0:32 offset1:48
	ds_read2_b32 v[156:157], v180 offset0:128 offset1:144
	ds_read2_b32 v[158:159], v180 offset0:160 offset1:176
	v_lshl_or_b32 v181, s52, 7, v148
	v_lshl_add_u32 v182, s18, 8, v144
	s_and_b64 vcc, exec, s[4:5]
	s_mov_b32 s52, s10
	s_mov_b32 s18, s12
	s_mov_b64 s[26:27], s[16:17]
	s_mov_b32 s51, s50
	s_mov_b64 s[20:21], s[14:15]
	v_mul_u32_u24_e32 v183, s49, v182
	v_lshl_add_u32 v183, v181, 1, v183
	s_waitcnt lgkmcnt(0)
	v_mul_f32_e32 v176, 0xbfb8aa3b, v152
	v_mul_f32_e32 v177, v152, v152
	v_rcp_f32_e32 v178, v177
	v_pk_mul_f32 v[160:161], v[124:125], v[176:177] op_sel_hi:[1,0]
	v_pk_mul_f32 v[162:163], v[126:127], v[176:177] op_sel_hi:[1,0]
	v_pk_mul_f32 v[164:165], v[120:121], v[176:177] op_sel_hi:[1,0]
	v_pk_mul_f32 v[166:167], v[122:123], v[176:177] op_sel_hi:[1,0]
	v_exp_f32_e32 v160, v160
	v_exp_f32_e32 v161, v161
	v_exp_f32_e32 v162, v162
	v_exp_f32_e32 v163, v163
	v_exp_f32_e32 v164, v164
	v_exp_f32_e32 v165, v165
	v_exp_f32_e32 v166, v166
	v_exp_f32_e32 v167, v167
	v_pk_fma_f32 v[160:161], v[160:161], v[178:179], v[178:179] op_sel_hi:[1,0,0]
	v_pk_fma_f32 v[162:163], v[162:163], v[178:179], v[178:179] op_sel_hi:[1,0,0]
	v_pk_fma_f32 v[164:165], v[164:165], v[178:179], v[178:179] op_sel_hi:[1,0,0]
	v_pk_fma_f32 v[166:167], v[166:167], v[178:179], v[178:179] op_sel_hi:[1,0,0]
	v_rcp_f32_e32 v160, v160
	v_rcp_f32_e32 v161, v161
	v_rcp_f32_e32 v162, v162
	v_rcp_f32_e32 v163, v163
	v_rcp_f32_e32 v164, v164
	v_rcp_f32_e32 v165, v165
	v_rcp_f32_e32 v166, v166
	v_rcp_f32_e32 v167, v167
	v_pk_mul_f32 v[124:125], v[124:125], v[116:117]
	v_pk_mul_f32 v[126:127], v[126:127], v[118:119]
	v_pk_mul_f32 v[120:121], v[120:121], v[112:113]
	v_pk_mul_f32 v[122:123], v[122:123], v[114:115]
	v_pk_mul_f32 v[124:125], v[124:125], v[160:161]
	v_pk_mul_f32 v[126:127], v[126:127], v[162:163]
	v_pk_mul_f32 v[120:121], v[120:121], v[164:165]
	v_pk_mul_f32 v[122:123], v[122:123], v[166:167]
	v_cvt_pk_bf16_f32 v168, v124, v125
	v_cvt_pk_bf16_f32 v169, v126, v127
	v_cvt_pk_bf16_f32 v170, v120, v121
	v_cvt_pk_bf16_f32 v171, v122, v123
	global_store_dwordx4 v183, v[168:171], s[6:7] nt
	v_mul_f32_e32 v176, 0xbfb8aa3b, v153
	v_mul_f32_e32 v177, v153, v153
	v_rcp_f32_e32 v178, v177
	v_pk_mul_f32 v[160:161], v[108:109], v[176:177] op_sel_hi:[1,0]
	v_pk_mul_f32 v[162:163], v[110:111], v[176:177] op_sel_hi:[1,0]
	v_pk_mul_f32 v[164:165], v[104:105], v[176:177] op_sel_hi:[1,0]
	v_pk_mul_f32 v[166:167], v[106:107], v[176:177] op_sel_hi:[1,0]
	v_exp_f32_e32 v160, v160
	v_exp_f32_e32 v161, v161
	v_exp_f32_e32 v162, v162
	v_exp_f32_e32 v163, v163
	v_exp_f32_e32 v164, v164
	v_exp_f32_e32 v165, v165
	v_exp_f32_e32 v166, v166
	v_exp_f32_e32 v167, v167
	v_pk_fma_f32 v[160:161], v[160:161], v[178:179], v[178:179] op_sel_hi:[1,0,0]
	v_pk_fma_f32 v[162:163], v[162:163], v[178:179], v[178:179] op_sel_hi:[1,0,0]
	v_pk_fma_f32 v[164:165], v[164:165], v[178:179], v[178:179] op_sel_hi:[1,0,0]
	v_pk_fma_f32 v[166:167], v[166:167], v[178:179], v[178:179] op_sel_hi:[1,0,0]
	v_rcp_f32_e32 v160, v160
	v_rcp_f32_e32 v161, v161
	v_rcp_f32_e32 v162, v162
	v_rcp_f32_e32 v163, v163
	v_rcp_f32_e32 v164, v164
	v_rcp_f32_e32 v165, v165
	v_rcp_f32_e32 v166, v166
	v_rcp_f32_e32 v167, v167
	v_pk_mul_f32 v[108:109], v[108:109], v[100:101]
	v_pk_mul_f32 v[110:111], v[110:111], v[102:103]
	v_pk_mul_f32 v[104:105], v[104:105], v[96:97]
	v_pk_mul_f32 v[106:107], v[106:107], v[98:99]
	v_pk_mul_f32 v[108:109], v[108:109], v[160:161]
	v_pk_mul_f32 v[110:111], v[110:111], v[162:163]
	v_pk_mul_f32 v[104:105], v[104:105], v[164:165]
	v_pk_mul_f32 v[106:107], v[106:107], v[166:167]
	v_cvt_pk_bf16_f32 v172, v108, v109
	v_cvt_pk_bf16_f32 v173, v110, v111
	v_cvt_pk_bf16_f32 v174, v104, v105
	v_cvt_pk_bf16_f32 v175, v106, v107
	v_add_u32_e32 v185, 0x16000, v183
	global_store_dwordx4 v185, v[172:175], s[6:7] nt
	v_mul_f32_e32 v176, 0xbfb8aa3b, v154
	v_mul_f32_e32 v177, v154, v154
	v_rcp_f32_e32 v178, v177
	v_pk_mul_f32 v[160:161], v[92:93], v[176:177] op_sel_hi:[1,0]
	v_pk_mul_f32 v[162:163], v[94:95], v[176:177] op_sel_hi:[1,0]
	v_pk_mul_f32 v[164:165], v[88:89], v[176:177] op_sel_hi:[1,0]
	v_pk_mul_f32 v[166:167], v[90:91], v[176:177] op_sel_hi:[1,0]
	v_exp_f32_e32 v160, v160
	v_exp_f32_e32 v161, v161
	v_exp_f32_e32 v162, v162
	v_exp_f32_e32 v163, v163
	v_exp_f32_e32 v164, v164
	v_exp_f32_e32 v165, v165
	v_exp_f32_e32 v166, v166
	v_exp_f32_e32 v167, v167
	v_pk_fma_f32 v[160:161], v[160:161], v[178:179], v[178:179] op_sel_hi:[1,0,0]
	v_pk_fma_f32 v[162:163], v[162:163], v[178:179], v[178:179] op_sel_hi:[1,0,0]
	v_pk_fma_f32 v[164:165], v[164:165], v[178:179], v[178:179] op_sel_hi:[1,0,0]
	v_pk_fma_f32 v[166:167], v[166:167], v[178:179], v[178:179] op_sel_hi:[1,0,0]
	v_rcp_f32_e32 v160, v160
	v_rcp_f32_e32 v161, v161
	v_rcp_f32_e32 v162, v162
	v_rcp_f32_e32 v163, v163
	v_rcp_f32_e32 v164, v164
	v_rcp_f32_e32 v165, v165
	v_rcp_f32_e32 v166, v166
	v_rcp_f32_e32 v167, v167
	v_pk_mul_f32 v[92:93], v[92:93], v[84:85]
	v_pk_mul_f32 v[94:95], v[94:95], v[86:87]
	v_pk_mul_f32 v[88:89], v[88:89], v[80:81]
	v_pk_mul_f32 v[90:91], v[90:91], v[82:83]
	v_pk_mul_f32 v[92:93], v[92:93], v[160:161]
	v_pk_mul_f32 v[94:95], v[94:95], v[162:163]
	v_pk_mul_f32 v[88:89], v[88:89], v[164:165]
	v_pk_mul_f32 v[90:91], v[90:91], v[166:167]
	v_cvt_pk_bf16_f32 v168, v92, v93
	v_cvt_pk_bf16_f32 v169, v94, v95
	v_cvt_pk_bf16_f32 v170, v88, v89
	v_cvt_pk_bf16_f32 v171, v90, v91
	v_add_u32_e32 v184, 0x2c000, v183
	global_store_dwordx4 v184, v[168:171], s[6:7] nt
	v_mul_f32_e32 v176, 0xbfb8aa3b, v155
	v_mul_f32_e32 v177, v155, v155
	v_rcp_f32_e32 v178, v177
	v_pk_mul_f32 v[160:161], v[76:77], v[176:177] op_sel_hi:[1,0]
	v_pk_mul_f32 v[162:163], v[78:79], v[176:177] op_sel_hi:[1,0]
	v_pk_mul_f32 v[164:165], v[72:73], v[176:177] op_sel_hi:[1,0]
	v_pk_mul_f32 v[166:167], v[74:75], v[176:177] op_sel_hi:[1,0]
	v_exp_f32_e32 v160, v160
	v_exp_f32_e32 v161, v161
	v_exp_f32_e32 v162, v162
	v_exp_f32_e32 v163, v163
	v_exp_f32_e32 v164, v164
	v_exp_f32_e32 v165, v165
	v_exp_f32_e32 v166, v166
	v_exp_f32_e32 v167, v167
	v_pk_fma_f32 v[160:161], v[160:161], v[178:179], v[178:179] op_sel_hi:[1,0,0]
	v_pk_fma_f32 v[162:163], v[162:163], v[178:179], v[178:179] op_sel_hi:[1,0,0]
	v_pk_fma_f32 v[164:165], v[164:165], v[178:179], v[178:179] op_sel_hi:[1,0,0]
	v_pk_fma_f32 v[166:167], v[166:167], v[178:179], v[178:179] op_sel_hi:[1,0,0]
	v_rcp_f32_e32 v160, v160
	v_rcp_f32_e32 v161, v161
	v_rcp_f32_e32 v162, v162
	v_rcp_f32_e32 v163, v163
	v_rcp_f32_e32 v164, v164
	v_rcp_f32_e32 v165, v165
	v_rcp_f32_e32 v166, v166
	v_rcp_f32_e32 v167, v167
	v_pk_mul_f32 v[76:77], v[76:77], v[68:69]
	v_pk_mul_f32 v[78:79], v[78:79], v[70:71]
	v_pk_mul_f32 v[72:73], v[72:73], v[64:65]
	v_pk_mul_f32 v[74:75], v[74:75], v[66:67]
	v_pk_mul_f32 v[76:77], v[76:77], v[160:161]
	v_pk_mul_f32 v[78:79], v[78:79], v[162:163]
	v_pk_mul_f32 v[72:73], v[72:73], v[164:165]
	v_pk_mul_f32 v[74:75], v[74:75], v[166:167]
	v_cvt_pk_bf16_f32 v172, v76, v77
	v_cvt_pk_bf16_f32 v173, v78, v79
	v_cvt_pk_bf16_f32 v174, v72, v73
	v_cvt_pk_bf16_f32 v175, v74, v75
	v_add_u32_e32 v185, 0x42000, v183
	global_store_dwordx4 v185, v[172:175], s[6:7] nt
	v_mul_f32_e32 v176, 0xbfb8aa3b, v156
	v_mul_f32_e32 v177, v156, v156
	v_rcp_f32_e32 v178, v177
	v_pk_mul_f32 v[160:161], v[60:61], v[176:177] op_sel_hi:[1,0]
	v_pk_mul_f32 v[162:163], v[62:63], v[176:177] op_sel_hi:[1,0]
	v_pk_mul_f32 v[164:165], v[56:57], v[176:177] op_sel_hi:[1,0]
	v_pk_mul_f32 v[166:167], v[58:59], v[176:177] op_sel_hi:[1,0]
	v_exp_f32_e32 v160, v160
	v_exp_f32_e32 v161, v161
	v_exp_f32_e32 v162, v162
	v_exp_f32_e32 v163, v163
	v_exp_f32_e32 v164, v164
	v_exp_f32_e32 v165, v165
	v_exp_f32_e32 v166, v166
	v_exp_f32_e32 v167, v167
	v_pk_fma_f32 v[160:161], v[160:161], v[178:179], v[178:179] op_sel_hi:[1,0,0]
	v_pk_fma_f32 v[162:163], v[162:163], v[178:179], v[178:179] op_sel_hi:[1,0,0]
	v_pk_fma_f32 v[164:165], v[164:165], v[178:179], v[178:179] op_sel_hi:[1,0,0]
	v_pk_fma_f32 v[166:167], v[166:167], v[178:179], v[178:179] op_sel_hi:[1,0,0]
	v_rcp_f32_e32 v160, v160
	v_rcp_f32_e32 v161, v161
	v_rcp_f32_e32 v162, v162
	v_rcp_f32_e32 v163, v163
	v_rcp_f32_e32 v164, v164
	v_rcp_f32_e32 v165, v165
	v_rcp_f32_e32 v166, v166
	v_rcp_f32_e32 v167, v167
	v_pk_mul_f32 v[60:61], v[60:61], v[52:53]
	v_pk_mul_f32 v[62:63], v[62:63], v[54:55]
	v_pk_mul_f32 v[56:57], v[56:57], v[48:49]
	v_pk_mul_f32 v[58:59], v[58:59], v[50:51]
	v_pk_mul_f32 v[60:61], v[60:61], v[160:161]
	v_pk_mul_f32 v[62:63], v[62:63], v[162:163]
	v_pk_mul_f32 v[56:57], v[56:57], v[164:165]
	v_pk_mul_f32 v[58:59], v[58:59], v[166:167]
	v_cvt_pk_bf16_f32 v168, v60, v61
	v_cvt_pk_bf16_f32 v169, v62, v63
	v_cvt_pk_bf16_f32 v170, v56, v57
	v_cvt_pk_bf16_f32 v171, v58, v59
	v_add_u32_e32 v184, 0xb0000, v183
	global_store_dwordx4 v184, v[168:171], s[6:7] nt
	v_mul_f32_e32 v176, 0xbfb8aa3b, v157
	v_mul_f32_e32 v177, v157, v157
	v_rcp_f32_e32 v178, v177
	v_pk_mul_f32 v[160:161], v[44:45], v[176:177] op_sel_hi:[1,0]
	v_pk_mul_f32 v[162:163], v[46:47], v[176:177] op_sel_hi:[1,0]
	v_pk_mul_f32 v[164:165], v[40:41], v[176:177] op_sel_hi:[1,0]
	v_pk_mul_f32 v[166:167], v[42:43], v[176:177] op_sel_hi:[1,0]
	v_exp_f32_e32 v160, v160
	v_exp_f32_e32 v161, v161
	v_exp_f32_e32 v162, v162
	v_exp_f32_e32 v163, v163
	v_exp_f32_e32 v164, v164
	v_exp_f32_e32 v165, v165
	v_exp_f32_e32 v166, v166
	v_exp_f32_e32 v167, v167
	v_pk_fma_f32 v[160:161], v[160:161], v[178:179], v[178:179] op_sel_hi:[1,0,0]
	v_pk_fma_f32 v[162:163], v[162:163], v[178:179], v[178:179] op_sel_hi:[1,0,0]
	v_pk_fma_f32 v[164:165], v[164:165], v[178:179], v[178:179] op_sel_hi:[1,0,0]
	v_pk_fma_f32 v[166:167], v[166:167], v[178:179], v[178:179] op_sel_hi:[1,0,0]
	v_rcp_f32_e32 v160, v160
	v_rcp_f32_e32 v161, v161
	v_rcp_f32_e32 v162, v162
	v_rcp_f32_e32 v163, v163
	v_rcp_f32_e32 v164, v164
	v_rcp_f32_e32 v165, v165
	v_rcp_f32_e32 v166, v166
	v_rcp_f32_e32 v167, v167
	v_pk_mul_f32 v[44:45], v[44:45], v[36:37]
	v_pk_mul_f32 v[46:47], v[46:47], v[38:39]
	v_pk_mul_f32 v[40:41], v[40:41], v[32:33]
	v_pk_mul_f32 v[42:43], v[42:43], v[34:35]
	v_pk_mul_f32 v[44:45], v[44:45], v[160:161]
	v_pk_mul_f32 v[46:47], v[46:47], v[162:163]
	v_pk_mul_f32 v[40:41], v[40:41], v[164:165]
	v_pk_mul_f32 v[42:43], v[42:43], v[166:167]
	v_cvt_pk_bf16_f32 v172, v44, v45
	v_cvt_pk_bf16_f32 v173, v46, v47
	v_cvt_pk_bf16_f32 v174, v40, v41
	v_cvt_pk_bf16_f32 v175, v42, v43
	v_add_u32_e32 v185, 0xc6000, v183
	global_store_dwordx4 v185, v[172:175], s[6:7] nt
	v_mul_f32_e32 v176, 0xbfb8aa3b, v158
	v_mul_f32_e32 v177, v158, v158
	v_rcp_f32_e32 v178, v177
	v_pk_mul_f32 v[160:161], v[28:29], v[176:177] op_sel_hi:[1,0]
	v_pk_mul_f32 v[162:163], v[30:31], v[176:177] op_sel_hi:[1,0]
	v_pk_mul_f32 v[164:165], v[24:25], v[176:177] op_sel_hi:[1,0]
	v_pk_mul_f32 v[166:167], v[26:27], v[176:177] op_sel_hi:[1,0]
	v_exp_f32_e32 v160, v160
	v_exp_f32_e32 v161, v161
	v_exp_f32_e32 v162, v162
	v_exp_f32_e32 v163, v163
	v_exp_f32_e32 v164, v164
	v_exp_f32_e32 v165, v165
	v_exp_f32_e32 v166, v166
	v_exp_f32_e32 v167, v167
	v_pk_fma_f32 v[160:161], v[160:161], v[178:179], v[178:179] op_sel_hi:[1,0,0]
	v_pk_fma_f32 v[162:163], v[162:163], v[178:179], v[178:179] op_sel_hi:[1,0,0]
	v_pk_fma_f32 v[164:165], v[164:165], v[178:179], v[178:179] op_sel_hi:[1,0,0]
	v_pk_fma_f32 v[166:167], v[166:167], v[178:179], v[178:179] op_sel_hi:[1,0,0]
	v_rcp_f32_e32 v160, v160
	v_rcp_f32_e32 v161, v161
	v_rcp_f32_e32 v162, v162
	v_rcp_f32_e32 v163, v163
	v_rcp_f32_e32 v164, v164
	v_rcp_f32_e32 v165, v165
	v_rcp_f32_e32 v166, v166
	v_rcp_f32_e32 v167, v167
	v_pk_mul_f32 v[28:29], v[28:29], v[20:21]
	v_pk_mul_f32 v[30:31], v[30:31], v[22:23]
	v_pk_mul_f32 v[24:25], v[24:25], v[16:17]
	v_pk_mul_f32 v[26:27], v[26:27], v[18:19]
	v_pk_mul_f32 v[28:29], v[28:29], v[160:161]
	v_pk_mul_f32 v[30:31], v[30:31], v[162:163]
	v_pk_mul_f32 v[24:25], v[24:25], v[164:165]
	v_pk_mul_f32 v[26:27], v[26:27], v[166:167]
	v_cvt_pk_bf16_f32 v168, v28, v29
	v_cvt_pk_bf16_f32 v169, v30, v31
	v_cvt_pk_bf16_f32 v170, v24, v25
	v_cvt_pk_bf16_f32 v171, v26, v27
	v_add_u32_e32 v184, 0xdc000, v183
	global_store_dwordx4 v184, v[168:171], s[6:7] nt
	v_mul_f32_e32 v176, 0xbfb8aa3b, v159
	v_mul_f32_e32 v177, v159, v159
	v_rcp_f32_e32 v178, v177
	v_pk_mul_f32 v[160:161], v[12:13], v[176:177] op_sel_hi:[1,0]
	v_pk_mul_f32 v[162:163], v[14:15], v[176:177] op_sel_hi:[1,0]
	v_pk_mul_f32 v[164:165], v[8:9], v[176:177] op_sel_hi:[1,0]
	v_pk_mul_f32 v[166:167], v[10:11], v[176:177] op_sel_hi:[1,0]
	v_exp_f32_e32 v160, v160
	v_exp_f32_e32 v161, v161
	v_exp_f32_e32 v162, v162
	v_exp_f32_e32 v163, v163
	v_exp_f32_e32 v164, v164
	v_exp_f32_e32 v165, v165
	v_exp_f32_e32 v166, v166
	v_exp_f32_e32 v167, v167
	v_pk_fma_f32 v[160:161], v[160:161], v[178:179], v[178:179] op_sel_hi:[1,0,0]
	v_pk_fma_f32 v[162:163], v[162:163], v[178:179], v[178:179] op_sel_hi:[1,0,0]
	v_pk_fma_f32 v[164:165], v[164:165], v[178:179], v[178:179] op_sel_hi:[1,0,0]
	v_pk_fma_f32 v[166:167], v[166:167], v[178:179], v[178:179] op_sel_hi:[1,0,0]
	v_rcp_f32_e32 v160, v160
	v_rcp_f32_e32 v161, v161
	v_rcp_f32_e32 v162, v162
	v_rcp_f32_e32 v163, v163
	v_rcp_f32_e32 v164, v164
	v_rcp_f32_e32 v165, v165
	v_rcp_f32_e32 v166, v166
	v_rcp_f32_e32 v167, v167
	v_pk_mul_f32 v[12:13], v[12:13], v[4:5]
	v_pk_mul_f32 v[14:15], v[14:15], v[6:7]
	v_pk_mul_f32 v[8:9], v[8:9], v[0:1]
	v_pk_mul_f32 v[10:11], v[10:11], v[2:3]
	v_pk_mul_f32 v[12:13], v[12:13], v[160:161]
	v_pk_mul_f32 v[14:15], v[14:15], v[162:163]
	v_pk_mul_f32 v[8:9], v[8:9], v[164:165]
	v_pk_mul_f32 v[10:11], v[10:11], v[166:167]
	v_cvt_pk_bf16_f32 v172, v12, v13
	v_cvt_pk_bf16_f32 v173, v14, v15
	v_cvt_pk_bf16_f32 v174, v8, v9
	v_cvt_pk_bf16_f32 v175, v10, v11
	v_add_u32_e32 v185, 0xf2000, v183
	global_store_dwordx4 v185, v[172:175], s[6:7] nt
	s_cbranch_vccz .LBB0_128
	s_waitcnt vmcnt(0)
	s_cmpk_gt_u32 s37, 0xff
	s_cbranch_scc1 .LBB0_135

.Lg893_nox:
	v_lshl_add_u32 v180, s51, 10, v146
	ds_read2_b32 v[152:153], v180 offset1:16
	ds_read2_b32 v[154:155], v180 offset0:32 offset1:48
	ds_read2_b32 v[156:157], v180 offset0:128 offset1:144
	ds_read2_b32 v[158:159], v180 offset0:160 offset1:176
	v_lshl_or_b32 v181, s52, 7, v147
	v_lshl_add_u32 v182, s18, 8, v144
	s_and_b64 vcc, exec, s[4:5]
	s_mov_b32 s52, s10
	s_mov_b32 s18, s12
	s_mov_b64 s[26:27], s[16:17]
	s_mov_b32 s51, s50
	s_mov_b64 s[20:21], s[14:15]
	v_mul_u32_u24_e32 v183, s49, v182
	v_lshl_add_u32 v183, v181, 1, v183
	s_waitcnt lgkmcnt(0)
	v_mul_f32_e32 v176, 0xbfb8aa3b, v152
	v_mul_f32_e32 v177, v152, v152
	v_rcp_f32_e32 v178, v177
	v_pk_mul_f32 v[160:161], v[124:125], v[176:177] op_sel_hi:[1,0]
	v_pk_mul_f32 v[162:163], v[126:127], v[176:177] op_sel_hi:[1,0]
	v_pk_mul_f32 v[164:165], v[120:121], v[176:177] op_sel_hi:[1,0]
	v_pk_mul_f32 v[166:167], v[122:123], v[176:177] op_sel_hi:[1,0]
	v_exp_f32_e32 v160, v160
	v_exp_f32_e32 v161, v161
	v_exp_f32_e32 v162, v162
	v_exp_f32_e32 v163, v163
	v_exp_f32_e32 v164, v164
	v_exp_f32_e32 v165, v165
	v_exp_f32_e32 v166, v166
	v_exp_f32_e32 v167, v167
	v_pk_fma_f32 v[160:161], v[160:161], v[178:179], v[178:179] op_sel_hi:[1,0,0]
	v_pk_fma_f32 v[162:163], v[162:163], v[178:179], v[178:179] op_sel_hi:[1,0,0]
	v_pk_fma_f32 v[164:165], v[164:165], v[178:179], v[178:179] op_sel_hi:[1,0,0]
	v_pk_fma_f32 v[166:167], v[166:167], v[178:179], v[178:179] op_sel_hi:[1,0,0]
	v_rcp_f32_e32 v160, v160
	v_rcp_f32_e32 v161, v161
	v_rcp_f32_e32 v162, v162
	v_rcp_f32_e32 v163, v163
	v_rcp_f32_e32 v164, v164
	v_rcp_f32_e32 v165, v165
	v_rcp_f32_e32 v166, v166
	v_rcp_f32_e32 v167, v167
	v_pk_mul_f32 v[124:125], v[124:125], v[116:117]
	v_pk_mul_f32 v[126:127], v[126:127], v[118:119]
	v_pk_mul_f32 v[120:121], v[120:121], v[112:113]
	v_pk_mul_f32 v[122:123], v[122:123], v[114:115]
	v_pk_mul_f32 v[124:125], v[124:125], v[160:161]
	v_pk_mul_f32 v[126:127], v[126:127], v[162:163]
	v_pk_mul_f32 v[120:121], v[120:121], v[164:165]
	v_pk_mul_f32 v[122:123], v[122:123], v[166:167]
	v_cvt_pk_bf16_f32 v168, v124, v125
	v_cvt_pk_bf16_f32 v169, v126, v127
	v_cvt_pk_bf16_f32 v170, v120, v121
	v_cvt_pk_bf16_f32 v171, v122, v123
	global_store_dwordx4 v183, v[168:171], s[6:7] nt
	v_mul_f32_e32 v176, 0xbfb8aa3b, v153
	v_mul_f32_e32 v177, v153, v153
	v_rcp_f32_e32 v178, v177
	v_pk_mul_f32 v[160:161], v[108:109], v[176:177] op_sel_hi:[1,0]
	v_pk_mul_f32 v[162:163], v[110:111], v[176:177] op_sel_hi:[1,0]
	v_pk_mul_f32 v[164:165], v[104:105], v[176:177] op_sel_hi:[1,0]
	v_pk_mul_f32 v[166:167], v[106:107], v[176:177] op_sel_hi:[1,0]
	v_exp_f32_e32 v160, v160
	v_exp_f32_e32 v161, v161
	v_exp_f32_e32 v162, v162
	v_exp_f32_e32 v163, v163
	v_exp_f32_e32 v164, v164
	v_exp_f32_e32 v165, v165
	v_exp_f32_e32 v166, v166
	v_exp_f32_e32 v167, v167
	v_pk_fma_f32 v[160:161], v[160:161], v[178:179], v[178:179] op_sel_hi:[1,0,0]
	v_pk_fma_f32 v[162:163], v[162:163], v[178:179], v[178:179] op_sel_hi:[1,0,0]
	v_pk_fma_f32 v[164:165], v[164:165], v[178:179], v[178:179] op_sel_hi:[1,0,0]
	v_pk_fma_f32 v[166:167], v[166:167], v[178:179], v[178:179] op_sel_hi:[1,0,0]
	v_rcp_f32_e32 v160, v160
	v_rcp_f32_e32 v161, v161
	v_rcp_f32_e32 v162, v162
	v_rcp_f32_e32 v163, v163
	v_rcp_f32_e32 v164, v164
	v_rcp_f32_e32 v165, v165
	v_rcp_f32_e32 v166, v166
	v_rcp_f32_e32 v167, v167
	v_pk_mul_f32 v[108:109], v[108:109], v[100:101]
	v_pk_mul_f32 v[110:111], v[110:111], v[102:103]
	v_pk_mul_f32 v[104:105], v[104:105], v[96:97]
	v_pk_mul_f32 v[106:107], v[106:107], v[98:99]
	v_pk_mul_f32 v[108:109], v[108:109], v[160:161]
	v_pk_mul_f32 v[110:111], v[110:111], v[162:163]
	v_pk_mul_f32 v[104:105], v[104:105], v[164:165]
	v_pk_mul_f32 v[106:107], v[106:107], v[166:167]
	v_cvt_pk_bf16_f32 v172, v108, v109
	v_cvt_pk_bf16_f32 v173, v110, v111
	v_cvt_pk_bf16_f32 v174, v104, v105
	v_cvt_pk_bf16_f32 v175, v106, v107
	v_add_u32_e32 v185, 0x16000, v183
	global_store_dwordx4 v185, v[172:175], s[6:7] nt
	v_mul_f32_e32 v176, 0xbfb8aa3b, v154
	v_mul_f32_e32 v177, v154, v154
	v_rcp_f32_e32 v178, v177
	v_pk_mul_f32 v[160:161], v[92:93], v[176:177] op_sel_hi:[1,0]
	v_pk_mul_f32 v[162:163], v[94:95], v[176:177] op_sel_hi:[1,0]
	v_pk_mul_f32 v[164:165], v[88:89], v[176:177] op_sel_hi:[1,0]
	v_pk_mul_f32 v[166:167], v[90:91], v[176:177] op_sel_hi:[1,0]
	v_exp_f32_e32 v160, v160
	v_exp_f32_e32 v161, v161
	v_exp_f32_e32 v162, v162
	v_exp_f32_e32 v163, v163
	v_exp_f32_e32 v164, v164
	v_exp_f32_e32 v165, v165
	v_exp_f32_e32 v166, v166
	v_exp_f32_e32 v167, v167
	v_pk_fma_f32 v[160:161], v[160:161], v[178:179], v[178:179] op_sel_hi:[1,0,0]
	v_pk_fma_f32 v[162:163], v[162:163], v[178:179], v[178:179] op_sel_hi:[1,0,0]
	v_pk_fma_f32 v[164:165], v[164:165], v[178:179], v[178:179] op_sel_hi:[1,0,0]
	v_pk_fma_f32 v[166:167], v[166:167], v[178:179], v[178:179] op_sel_hi:[1,0,0]
	v_rcp_f32_e32 v160, v160
	v_rcp_f32_e32 v161, v161
	v_rcp_f32_e32 v162, v162
	v_rcp_f32_e32 v163, v163
	v_rcp_f32_e32 v164, v164
	v_rcp_f32_e32 v165, v165
	v_rcp_f32_e32 v166, v166
	v_rcp_f32_e32 v167, v167
	v_pk_mul_f32 v[92:93], v[92:93], v[84:85]
	v_pk_mul_f32 v[94:95], v[94:95], v[86:87]
	v_pk_mul_f32 v[88:89], v[88:89], v[80:81]
	v_pk_mul_f32 v[90:91], v[90:91], v[82:83]
	v_pk_mul_f32 v[92:93], v[92:93], v[160:161]
	v_pk_mul_f32 v[94:95], v[94:95], v[162:163]
	v_pk_mul_f32 v[88:89], v[88:89], v[164:165]
	v_pk_mul_f32 v[90:91], v[90:91], v[166:167]
	v_cvt_pk_bf16_f32 v168, v92, v93
	v_cvt_pk_bf16_f32 v169, v94, v95
	v_cvt_pk_bf16_f32 v170, v88, v89
	v_cvt_pk_bf16_f32 v171, v90, v91
	v_add_u32_e32 v184, 0x2c000, v183
	global_store_dwordx4 v184, v[168:171], s[6:7] nt
	v_mul_f32_e32 v176, 0xbfb8aa3b, v155
	v_mul_f32_e32 v177, v155, v155
	v_rcp_f32_e32 v178, v177
	v_pk_mul_f32 v[160:161], v[76:77], v[176:177] op_sel_hi:[1,0]
	v_pk_mul_f32 v[162:163], v[78:79], v[176:177] op_sel_hi:[1,0]
	v_pk_mul_f32 v[164:165], v[72:73], v[176:177] op_sel_hi:[1,0]
	v_pk_mul_f32 v[166:167], v[74:75], v[176:177] op_sel_hi:[1,0]
	v_exp_f32_e32 v160, v160
	v_exp_f32_e32 v161, v161
	v_exp_f32_e32 v162, v162
	v_exp_f32_e32 v163, v163
	v_exp_f32_e32 v164, v164
	v_exp_f32_e32 v165, v165
	v_exp_f32_e32 v166, v166
	v_exp_f32_e32 v167, v167
	v_pk_fma_f32 v[160:161], v[160:161], v[178:179], v[178:179] op_sel_hi:[1,0,0]
	v_pk_fma_f32 v[162:163], v[162:163], v[178:179], v[178:179] op_sel_hi:[1,0,0]
	v_pk_fma_f32 v[164:165], v[164:165], v[178:179], v[178:179] op_sel_hi:[1,0,0]
	v_pk_fma_f32 v[166:167], v[166:167], v[178:179], v[178:179] op_sel_hi:[1,0,0]
	v_rcp_f32_e32 v160, v160
	v_rcp_f32_e32 v161, v161
	v_rcp_f32_e32 v162, v162
	v_rcp_f32_e32 v163, v163
	v_rcp_f32_e32 v164, v164
	v_rcp_f32_e32 v165, v165
	v_rcp_f32_e32 v166, v166
	v_rcp_f32_e32 v167, v167
	v_pk_mul_f32 v[76:77], v[76:77], v[68:69]
	v_pk_mul_f32 v[78:79], v[78:79], v[70:71]
	v_pk_mul_f32 v[72:73], v[72:73], v[64:65]
	v_pk_mul_f32 v[74:75], v[74:75], v[66:67]
	v_pk_mul_f32 v[76:77], v[76:77], v[160:161]
	v_pk_mul_f32 v[78:79], v[78:79], v[162:163]
	v_pk_mul_f32 v[72:73], v[72:73], v[164:165]
	v_pk_mul_f32 v[74:75], v[74:75], v[166:167]
	v_cvt_pk_bf16_f32 v172, v76, v77
	v_cvt_pk_bf16_f32 v173, v78, v79
	v_cvt_pk_bf16_f32 v174, v72, v73
	v_cvt_pk_bf16_f32 v175, v74, v75
	v_add_u32_e32 v185, 0x42000, v183
	global_store_dwordx4 v185, v[172:175], s[6:7] nt
	v_mul_f32_e32 v176, 0xbfb8aa3b, v156
	v_mul_f32_e32 v177, v156, v156
	v_rcp_f32_e32 v178, v177
	v_pk_mul_f32 v[160:161], v[60:61], v[176:177] op_sel_hi:[1,0]
	v_pk_mul_f32 v[162:163], v[62:63], v[176:177] op_sel_hi:[1,0]
	v_pk_mul_f32 v[164:165], v[56:57], v[176:177] op_sel_hi:[1,0]
	v_pk_mul_f32 v[166:167], v[58:59], v[176:177] op_sel_hi:[1,0]
	v_exp_f32_e32 v160, v160
	v_exp_f32_e32 v161, v161
	v_exp_f32_e32 v162, v162
	v_exp_f32_e32 v163, v163
	v_exp_f32_e32 v164, v164
	v_exp_f32_e32 v165, v165
	v_exp_f32_e32 v166, v166
	v_exp_f32_e32 v167, v167
	v_pk_fma_f32 v[160:161], v[160:161], v[178:179], v[178:179] op_sel_hi:[1,0,0]
	v_pk_fma_f32 v[162:163], v[162:163], v[178:179], v[178:179] op_sel_hi:[1,0,0]
	v_pk_fma_f32 v[164:165], v[164:165], v[178:179], v[178:179] op_sel_hi:[1,0,0]
	v_pk_fma_f32 v[166:167], v[166:167], v[178:179], v[178:179] op_sel_hi:[1,0,0]
	v_rcp_f32_e32 v160, v160
	v_rcp_f32_e32 v161, v161
	v_rcp_f32_e32 v162, v162
	v_rcp_f32_e32 v163, v163
	v_rcp_f32_e32 v164, v164
	v_rcp_f32_e32 v165, v165
	v_rcp_f32_e32 v166, v166
	v_rcp_f32_e32 v167, v167
	v_pk_mul_f32 v[60:61], v[60:61], v[52:53]
	v_pk_mul_f32 v[62:63], v[62:63], v[54:55]
	v_pk_mul_f32 v[56:57], v[56:57], v[48:49]
	v_pk_mul_f32 v[58:59], v[58:59], v[50:51]
	v_pk_mul_f32 v[60:61], v[60:61], v[160:161]
	v_pk_mul_f32 v[62:63], v[62:63], v[162:163]
	v_pk_mul_f32 v[56:57], v[56:57], v[164:165]
	v_pk_mul_f32 v[58:59], v[58:59], v[166:167]
	v_cvt_pk_bf16_f32 v168, v60, v61
	v_cvt_pk_bf16_f32 v169, v62, v63
	v_cvt_pk_bf16_f32 v170, v56, v57
	v_cvt_pk_bf16_f32 v171, v58, v59
	v_add_u32_e32 v184, 0xb0000, v183
	global_store_dwordx4 v184, v[168:171], s[6:7] nt
	v_mul_f32_e32 v176, 0xbfb8aa3b, v157
	v_mul_f32_e32 v177, v157, v157
	v_rcp_f32_e32 v178, v177
	v_pk_mul_f32 v[160:161], v[44:45], v[176:177] op_sel_hi:[1,0]
	v_pk_mul_f32 v[162:163], v[46:47], v[176:177] op_sel_hi:[1,0]
	v_pk_mul_f32 v[164:165], v[40:41], v[176:177] op_sel_hi:[1,0]
	v_pk_mul_f32 v[166:167], v[42:43], v[176:177] op_sel_hi:[1,0]
	v_exp_f32_e32 v160, v160
	v_exp_f32_e32 v161, v161
	v_exp_f32_e32 v162, v162
	v_exp_f32_e32 v163, v163
	v_exp_f32_e32 v164, v164
	v_exp_f32_e32 v165, v165
	v_exp_f32_e32 v166, v166
	v_exp_f32_e32 v167, v167
	v_pk_fma_f32 v[160:161], v[160:161], v[178:179], v[178:179] op_sel_hi:[1,0,0]
	v_pk_fma_f32 v[162:163], v[162:163], v[178:179], v[178:179] op_sel_hi:[1,0,0]
	v_pk_fma_f32 v[164:165], v[164:165], v[178:179], v[178:179] op_sel_hi:[1,0,0]
	v_pk_fma_f32 v[166:167], v[166:167], v[178:179], v[178:179] op_sel_hi:[1,0,0]
	v_rcp_f32_e32 v160, v160
	v_rcp_f32_e32 v161, v161
	v_rcp_f32_e32 v162, v162
	v_rcp_f32_e32 v163, v163
	v_rcp_f32_e32 v164, v164
	v_rcp_f32_e32 v165, v165
	v_rcp_f32_e32 v166, v166
	v_rcp_f32_e32 v167, v167
	v_pk_mul_f32 v[44:45], v[44:45], v[36:37]
	v_pk_mul_f32 v[46:47], v[46:47], v[38:39]
	v_pk_mul_f32 v[40:41], v[40:41], v[32:33]
	v_pk_mul_f32 v[42:43], v[42:43], v[34:35]
	v_pk_mul_f32 v[44:45], v[44:45], v[160:161]
	v_pk_mul_f32 v[46:47], v[46:47], v[162:163]
	v_pk_mul_f32 v[40:41], v[40:41], v[164:165]
	v_pk_mul_f32 v[42:43], v[42:43], v[166:167]
	v_cvt_pk_bf16_f32 v172, v44, v45
	v_cvt_pk_bf16_f32 v173, v46, v47
	v_cvt_pk_bf16_f32 v174, v40, v41
	v_cvt_pk_bf16_f32 v175, v42, v43
	v_add_u32_e32 v185, 0xc6000, v183
	global_store_dwordx4 v185, v[172:175], s[6:7] nt
	v_mul_f32_e32 v176, 0xbfb8aa3b, v158
	v_mul_f32_e32 v177, v158, v158
	v_rcp_f32_e32 v178, v177
	v_pk_mul_f32 v[160:161], v[28:29], v[176:177] op_sel_hi:[1,0]
	v_pk_mul_f32 v[162:163], v[30:31], v[176:177] op_sel_hi:[1,0]
	v_pk_mul_f32 v[164:165], v[24:25], v[176:177] op_sel_hi:[1,0]
	v_pk_mul_f32 v[166:167], v[26:27], v[176:177] op_sel_hi:[1,0]
	v_exp_f32_e32 v160, v160
	v_exp_f32_e32 v161, v161
	v_exp_f32_e32 v162, v162
	v_exp_f32_e32 v163, v163
	v_exp_f32_e32 v164, v164
	v_exp_f32_e32 v165, v165
	v_exp_f32_e32 v166, v166
	v_exp_f32_e32 v167, v167
	v_pk_fma_f32 v[160:161], v[160:161], v[178:179], v[178:179] op_sel_hi:[1,0,0]
	v_pk_fma_f32 v[162:163], v[162:163], v[178:179], v[178:179] op_sel_hi:[1,0,0]
	v_pk_fma_f32 v[164:165], v[164:165], v[178:179], v[178:179] op_sel_hi:[1,0,0]
	v_pk_fma_f32 v[166:167], v[166:167], v[178:179], v[178:179] op_sel_hi:[1,0,0]
	v_rcp_f32_e32 v160, v160
	v_rcp_f32_e32 v161, v161
	v_rcp_f32_e32 v162, v162
	v_rcp_f32_e32 v163, v163
	v_rcp_f32_e32 v164, v164
	v_rcp_f32_e32 v165, v165
	v_rcp_f32_e32 v166, v166
	v_rcp_f32_e32 v167, v167
	v_pk_mul_f32 v[28:29], v[28:29], v[20:21]
	v_pk_mul_f32 v[30:31], v[30:31], v[22:23]
	v_pk_mul_f32 v[24:25], v[24:25], v[16:17]
	v_pk_mul_f32 v[26:27], v[26:27], v[18:19]
	v_pk_mul_f32 v[28:29], v[28:29], v[160:161]
	v_pk_mul_f32 v[30:31], v[30:31], v[162:163]
	v_pk_mul_f32 v[24:25], v[24:25], v[164:165]
	v_pk_mul_f32 v[26:27], v[26:27], v[166:167]
	v_cvt_pk_bf16_f32 v168, v28, v29
	v_cvt_pk_bf16_f32 v169, v30, v31
	v_cvt_pk_bf16_f32 v170, v24, v25
	v_cvt_pk_bf16_f32 v171, v26, v27
	v_add_u32_e32 v184, 0xdc000, v183
	global_store_dwordx4 v184, v[168:171], s[6:7] nt
	v_mul_f32_e32 v176, 0xbfb8aa3b, v159
	v_mul_f32_e32 v177, v159, v159
	v_rcp_f32_e32 v178, v177
	v_pk_mul_f32 v[160:161], v[12:13], v[176:177] op_sel_hi:[1,0]
	v_pk_mul_f32 v[162:163], v[14:15], v[176:177] op_sel_hi:[1,0]
	v_pk_mul_f32 v[164:165], v[8:9], v[176:177] op_sel_hi:[1,0]
	v_pk_mul_f32 v[166:167], v[10:11], v[176:177] op_sel_hi:[1,0]
	v_exp_f32_e32 v160, v160
	v_exp_f32_e32 v161, v161
	v_exp_f32_e32 v162, v162
	v_exp_f32_e32 v163, v163
	v_exp_f32_e32 v164, v164
	v_exp_f32_e32 v165, v165
	v_exp_f32_e32 v166, v166
	v_exp_f32_e32 v167, v167
	v_pk_fma_f32 v[160:161], v[160:161], v[178:179], v[178:179] op_sel_hi:[1,0,0]
	v_pk_fma_f32 v[162:163], v[162:163], v[178:179], v[178:179] op_sel_hi:[1,0,0]
	v_pk_fma_f32 v[164:165], v[164:165], v[178:179], v[178:179] op_sel_hi:[1,0,0]
	v_pk_fma_f32 v[166:167], v[166:167], v[178:179], v[178:179] op_sel_hi:[1,0,0]
	v_rcp_f32_e32 v160, v160
	v_rcp_f32_e32 v161, v161
	v_rcp_f32_e32 v162, v162
	v_rcp_f32_e32 v163, v163
	v_rcp_f32_e32 v164, v164
	v_rcp_f32_e32 v165, v165
	v_rcp_f32_e32 v166, v166
	v_rcp_f32_e32 v167, v167
	v_pk_mul_f32 v[12:13], v[12:13], v[4:5]
	v_pk_mul_f32 v[14:15], v[14:15], v[6:7]
	v_pk_mul_f32 v[8:9], v[8:9], v[0:1]
	v_pk_mul_f32 v[10:11], v[10:11], v[2:3]
	v_pk_mul_f32 v[12:13], v[12:13], v[160:161]
	v_pk_mul_f32 v[14:15], v[14:15], v[162:163]
	v_pk_mul_f32 v[8:9], v[8:9], v[164:165]
	v_pk_mul_f32 v[10:11], v[10:11], v[166:167]
	v_cvt_pk_bf16_f32 v172, v12, v13
	v_cvt_pk_bf16_f32 v173, v14, v15
	v_cvt_pk_bf16_f32 v174, v8, v9
	v_cvt_pk_bf16_f32 v175, v10, v11
	v_add_u32_e32 v185, 0xf2000, v183
	global_store_dwordx4 v185, v[172:175], s[6:7] nt
	s_cbranch_vccz .LBB0_890
	s_waitcnt vmcnt(0)
	s_cmpk_gt_u32 s30, 0xff
	s_cbranch_scc1 .LBB0_897
